# P1: ctx projection before the GEMM stream only for the late half (2 sleeps left), after the last tile for the other half
# speedup vs baseline: 1.0075x; 1.0070x over previous
; #define RUNPH(n, ...) do { REFRESH(); { __VA_ARGS__ } if ((DUPMASK >> (n)) & 1) { grid.sync(); REFRESH(); { __VA_ARGS__ } } } while (0)
; __device__ __forceinline__ void ctx_in_gemm(Frame& F) {
;     const int w = F.bx * NWAVES + F.wave; if (w >= 2048) return;
;     const int rt = w >> 6, ct = w & 63, l15 = F.lane & 15, q = F.lane >> 4;
;     const bf16* A = (const bf16*)(F.ws + WS_NCTX) + (size_t)(rt * 16 + l15) * D + 8 * q;
;     const bf16* B0 = (const bf16*)(F.ws + WS_WIN) + (size_t)(ct * 32 + l15) * D + 8 * q;
;     const bf16* B1 = B0 + (size_t)16 * D;
;     f32x4 a0 = {0, 0, 0, 0}, a1 = a0;
; __global__ void __launch_bounds__(NTHREADS, 2) fwd_megakernel(Params p) {
;     ...
;     RUNPH(2, ctx_in_gemm(F);
;         { const int nsl = ((F.bx >> P1_SHIFT) & P1_GROUPS) * P1_STAGGER; for (int i = 0; i < nsl; ++i) __builtin_amdgcn_s_sleep(127); }
.LBB0_368:
	s_or_b64 exec, exec, s[4:5]
	s_cmpk_gt_i32 s60, 0x7ff
	s_waitcnt lgkmcnt(0)
	s_barrier
	v_mbcnt_lo_u32_b32 v0, -1, 0
	v_mbcnt_hi_u32_b32 v0, -1, v0
	s_mov_b32 s98, 0
	s_bitcmp1_b32 s2, 3
	s_cbranch_scc0 .LBB0_403
	s_cmpk_gt_i32 s60, 0x7ff
	s_cbranch_scc1 .LBB0_403
.Lmy_ctx_entry:
	s_ashr_i32 s4, s60, 2
	v_and_b32_e32 v18, 15, v0
	v_ashrrev_i32_e32 v12, 4, v0
	s_and_b32 s6, s4, -16
	v_bfi_b32 v0, 15, v0, s4
	s_lshl_b32 s4, s60, 5
	v_lshlrev_b32_e32 v2, 3, v12
	s_and_b32 s10, s4, 0x7e0
	v_ashrrev_i32_e32 v1, 31, v0
	v_ashrrev_i32_e32 v3, 31, v2
	v_or_b32_e32 v13, s10, v18
	v_lshlrev_b64 v[0:1], 12, v[0:1]
	v_lshlrev_b64 v[2:3], 1, v[2:3]
	v_lshlrev_b32_e32 v4, 12, v13
	v_mov_b32_e32 v5, 0
	v_lshl_add_u64 v[6:7], v[2:3], 0, v[4:5]
	v_lshl_add_u64 v[0:1], v[0:1], 0, v[2:3]
	v_lshl_add_u64 v[8:9], s[56:57], 0, v[6:7]
	v_lshl_add_u64 v[10:11], s[56:57], 0, v[0:1]
	s_mov_b64 s[4:5], 0
	v_mov_b32_e32 v4, v5
	v_mov_b32_e32 v6, v5
	v_mov_b32_e32 v7, v5
	v_mov_b32_e32 v0, v5
	v_mov_b32_e32 v1, v5
	v_mov_b32_e32 v2, v5
	v_mov_b32_e32 v3, v5

; #define REFRESH() do { F.lane = lane_id(); F.tid = F.wave * 64 + F.lane; } while (0)
; #define RUNPH(n, ...) do { REFRESH(); { __VA_ARGS__ } if ((DUPMASK >> (n)) & 1) { grid.sync(); REFRESH(); { __VA_ARGS__ } } } while (0)
; __global__ void __launch_bounds__(NTHREADS, 2) fwd_megakernel(Params p) {
;     ...
;     RUNPH(2, ctx_in_gemm(F);
;         { const int nsl = ((F.bx >> P1_SHIFT) & P1_GROUPS) * P1_STAGGER; for (int i = 0; i < nsl; ++i) __builtin_amdgcn_s_sleep(127); }
;         REFRESH();
.LBB0_403:
	s_cmp_eq_u32 s98, 1
	s_cbranch_scc1 .Lmy_p1_tail
	s_and_b32 s4, s2, 8
	s_bitcmp1_b32 s2, 3
	s_cselect_b64 s[36:37], -1, 0
	s_cmp_eq_u32 s4, 0
	s_mov_b64 s[4:5], 0
	s_cbranch_scc1 .LBB0_405
	s_mov_b64 s[4:5], 13
	s_sleep 0x7f
	s_sleep 0x7f

; #define REFRESH() do { F.lane = lane_id(); F.tid = F.wave * 64 + F.lane; } while (0)
; #define RUNPH(n, ...) do { REFRESH(); { __VA_ARGS__ } if ((DUPMASK >> (n)) & 1) { grid.sync(); REFRESH(); { __VA_ARGS__ } } } while (0)
; __global__ void __launch_bounds__(NTHREADS, 2) fwd_megakernel(Params p) {
;     ...
;     RUNPH(2, ctx_in_gemm(F);
;         { const int nsl = ((F.bx >> P1_SHIFT) & P1_GROUPS) * P1_STAGGER; for (int i = 0; i < nsl; ++i) __builtin_amdgcn_s_sleep(127); }
;         REFRESH();
;         pg8::Sched S; S.A = (const char*)(F.ws + WS_NBUF8); S.B = (const char*)(F.ws + WS_WINI8); S.gA = 0; S.gB = 0; S.lda = D; S.ldb = D; S.nM = NTOK / 256; S.nN = INW / 256; S.nG = 1; S.G = F.G; S.c = F.bx;
;         S.A2 = S.A; S.B2 = S.B; S.pair = 0; S.esz = 1; S.rev = 0; S.nper = 0;
;         S.rev = P1_REV ? ((F.bx >> 3) & 1) : 0; S.nper = (NTOK / 256) * (INW / 256) / 256;
;         pg8::Epi E; E.mode = pg8::EM_IN; E.ws = F.ws; E.x = p.in[0]; E.out = p.out; E.modf = (const float*)(F.ws + WS_MODF);
;         pg8::gemm_phase<true>(F.lds, D, S, E, F.wave););
.LBB0_588:
	s_bitcmp1_b32 s2, 3
	s_cbranch_scc1 .Lmy_p1_tail
	s_cmp_eq_u32 s98, 1
	s_cbranch_scc1 .Lmy_p1_tail
	s_mov_b32 s98, 1
	s_mov_b64 exec, -1
	v_mbcnt_lo_u32_b32 v0, -1, 0
	v_mbcnt_hi_u32_b32 v0, -1, v0
	s_cmpk_gt_i32 s60, 0x7ff
	s_cbranch_scc1 .Lmy_p1_tail
	s_branch .Lmy_ctx_entry

; #define LAS __attribute__((address_space(3)))
; __global__ void __launch_bounds__(NTHREADS, 2) fwd_megakernel(Params p) {
;     extern __shared__ __attribute__((aligned(16))) unsigned char lds_raw[];
;     cg::grid_group grid = cg::this_grid();
;     Frame F; F.lds = (LAS unsigned char*)lds_raw; F.tid = threadIdx.x; F.lane = F.tid & 63; F.wave = __builtin_amdgcn_readfirstlane(F.tid >> 6); F.G = gridDim.x; F.bx = blockIdx.x; F.ws = p.ws;
	.amdhsa_kernel _Z14fwd_megakernel6Params
		.amdhsa_group_segment_fixed_size 0
		.amdhsa_private_segment_fixed_size 0
		.amdhsa_kernarg_size 536
		.amdhsa_user_sgpr_count 2
		.amdhsa_user_sgpr_dispatch_ptr 0
		.amdhsa_user_sgpr_queue_ptr 0
		.amdhsa_user_sgpr_kernarg_segment_ptr 1
		.amdhsa_user_sgpr_dispatch_id 0
		.amdhsa_user_sgpr_kernarg_preload_length 0
		.amdhsa_user_sgpr_kernarg_preload_offset 0
		.amdhsa_user_sgpr_private_segment_size 0
		.amdhsa_uses_dynamic_stack 0
		.amdhsa_enable_private_segment 0
		.amdhsa_system_sgpr_workgroup_id_x 1
		.amdhsa_system_sgpr_workgroup_id_y 0
		.amdhsa_system_sgpr_workgroup_id_z 0
		.amdhsa_system_sgpr_workgroup_info 0
		.amdhsa_system_vgpr_workitem_id 2
		.amdhsa_next_free_vgpr 240
		.amdhsa_next_free_sgpr 102
		.amdhsa_accum_offset 240
		.amdhsa_reserve_vcc 1
		.amdhsa_float_round_mode_32 0
		.amdhsa_float_round_mode_16_64 0
		.amdhsa_float_denorm_mode_32 3
		.amdhsa_float_denorm_mode_16_64 3
		.amdhsa_dx10_clamp 1
		.amdhsa_ieee_mode 1
		.amdhsa_fp16_overflow 0
		.amdhsa_tg_split 0
		.amdhsa_exception_fp_ieee_invalid_op 0
		.amdhsa_exception_fp_denorm_src 0
		.amdhsa_exception_fp_ieee_div_zero 0
		.amdhsa_exception_fp_ieee_overflow 0
		.amdhsa_exception_fp_ieee_underflow 0
		.amdhsa_exception_fp_ieee_inexact 0
		.amdhsa_exception_int_div_zero 0
	.end_amdhsa_kernel

; #define LAS __attribute__((address_space(3)))
; __device__ __forceinline__ unsigned xb_add(unsigned* p, unsigned v) { return __hip_atomic_fetch_add(p, v, __ATOMIC_RELAXED, __HIP_MEMORY_SCOPE_AGENT); }
; __global__ void __launch_bounds__(NTHREADS, 2) fwd_megakernel(Params p) {
;     extern __shared__ __attribute__((aligned(16))) unsigned char lds_raw[];
;     cg::grid_group grid = cg::this_grid();
;     Frame F; F.lds = (LAS unsigned char*)lds_raw; F.tid = threadIdx.x; F.lane = F.tid & 63; F.wave = __builtin_amdgcn_readfirstlane(F.tid >> 6); F.G = gridDim.x; F.bx = blockIdx.x; F.ws = p.ws;
;     volatile LAS unsigned* bst = (volatile LAS unsigned*)(F.lds + LDS_BYTES - 16);
;     if (F.tid < 4) bst[F.tid] = 0u;
;     __syncthreads();
;     const XcdBarrier xbar = xcd_barrier_post((unsigned*)(p.ws), bst, F.tid == 0);
;     if (F.tid == 0) { bst[2] = xb_add((unsigned*)p.ws + CW_RANK + 64 * xbar.x, 1u); bst[3] = xb_add((unsigned*)p.ws + CW_TICKET, 1u); }
amdhsa.kernels:
  - .agpr_count:     0
    .args:
      - .offset:         0
        .size:           280
        .value_kind:     by_value
      - .offset:         280
        .size:           4
        .value_kind:     hidden_block_count_x
      - .offset:         284
        .size:           4
        .value_kind:     hidden_block_count_y
      - .offset:         288
        .size:           4
        .value_kind:     hidden_block_count_z
      - .offset:         292
        .size:           2
        .value_kind:     hidden_group_size_x
      - .offset:         294
        .size:           2
        .value_kind:     hidden_group_size_y
      - .offset:         296
        .size:           2
        .value_kind:     hidden_group_size_z
      - .offset:         298
        .size:           2
        .value_kind:     hidden_remainder_x
      - .offset:         300
        .size:           2
        .value_kind:     hidden_remainder_y
      - .offset:         302
        .size:           2
        .value_kind:     hidden_remainder_z
      - .offset:         320
        .size:           8
        .value_kind:     hidden_global_offset_x
      - .offset:         328
        .size:           8
        .value_kind:     hidden_global_offset_y
      - .offset:         336
        .size:           8
        .value_kind:     hidden_global_offset_z
      - .offset:         344
        .size:           2
        .value_kind:     hidden_grid_dims
      - .offset:         368
        .size:           8
        .value_kind:     hidden_multigrid_sync_arg
      - .offset:         400
        .size:           4
        .value_kind:     hidden_dynamic_lds_size
    .group_segment_fixed_size: 0
    .kernarg_segment_align: 8
    .kernarg_segment_size: 536
    .language:       OpenCL C
    .language_version:
      - 2
      - 0
    .max_flat_workgroup_size: 512
    .name:           _Z14fwd_megakernel6Params
    .private_segment_fixed_size: 0
    .sgpr_count:     108
    .sgpr_spill_count: 4
    .symbol:         _Z14fwd_megakernel6Params.kd
    .uniform_work_group_size: 1
    .uses_dynamic_stack: false
    .vgpr_count:     240
    .vgpr_spill_count: 0
    .wavefront_size: 64
